# v1 plus 20 bytes of padding after the attention loop so later phases keep the baseline cache-line alignment
# baseline (speedup 1.0000x reference)
.LBB0_311:
	s_mov_b32 s37, s36
	s_mov_b32 s4, s33
	s_mov_b32 s1, s42
	v_add_u32_e32 v209, s5, v252
	ds_read_b64_tr_b16 v[216:217], v209 offset:24576
	ds_read_b64_tr_b16 v[218:219], v209 offset:25088
	v_add_f32_e32 v65, v96, v97
	v_add_f32_e32 v65, v98, v65
	v_add_f32_e32 v65, v99, v65
	v_add_f32_e32 v65, v100, v65
	v_add_f32_e32 v65, v101, v65
	v_cvt_pk_bf16_f32 v172, v96, v97
	v_cvt_pk_bf16_f32 v173, v98, v99
	s_waitcnt lgkmcnt(9)
	v_mfma_f32_32x32x16_bf16 v[128:143], v[204:207], v[156:159], v[230:245]
	ds_read_b64_tr_b16 v[204:205], v209 offset:28672
	ds_read_b64_tr_b16 v[206:207], v209 offset:29184
	v_add_f32_e32 v65, v102, v65
	v_add_f32_e32 v65, v103, v65
	v_add_f32_e32 v65, v104, v65
	v_add_f32_e32 v65, v105, v65
	v_cvt_pk_bf16_f32 v174, v100, v101
	v_cvt_pk_bf16_f32 v175, v102, v103
	s_waitcnt lgkmcnt(10)
	v_mfma_f32_32x32x16_bf16 v[112:127], v[200:203], v[156:159], v[230:245]
	ds_read_b64_tr_b16 v[74:75], v209 offset:25600
	ds_read_b64_tr_b16 v[76:77], v209 offset:26112
	v_add_f32_e32 v65, v106, v65
	v_add_f32_e32 v65, v107, v65
	v_add_f32_e32 v65, v108, v65
	v_add_f32_e32 v65, v109, v65
	v_cvt_pk_bf16_f32 v168, v104, v105
	v_cvt_pk_bf16_f32 v169, v106, v107
	s_waitcnt lgkmcnt(11)
	v_mfma_f32_32x32x16_bf16 v[128:143], v[196:199], v[152:155], v[128:143]
	ds_read_b64_tr_b16 v[70:71], v209 offset:29696
	ds_read_b64_tr_b16 v[72:73], v209 offset:30208
	v_add_f32_e32 v65, v110, v65
	v_add_f32_e32 v65, v111, v65
	v_add_f32_e32 v65, v80, v65
	v_add_f32_e32 v65, v81, v65
	v_cvt_pk_bf16_f32 v170, v108, v109
	v_cvt_pk_bf16_f32 v171, v110, v111
	s_waitcnt lgkmcnt(12)
	v_mfma_f32_32x32x16_bf16 v[112:127], v[192:195], v[152:155], v[112:127]
	ds_read_b64_tr_b16 v[66:67], v209 offset:26624
	ds_read_b64_tr_b16 v[68:69], v209 offset:27136
	v_add_f32_e32 v65, v82, v65
	v_add_f32_e32 v65, v83, v65
	v_add_f32_e32 v65, v84, v65
	v_add_f32_e32 v65, v85, v65
	v_cvt_pk_bf16_f32 v164, v80, v81
	v_cvt_pk_bf16_f32 v165, v82, v83
	s_waitcnt lgkmcnt(13)
	v_mfma_f32_32x32x16_bf16 v[128:143], v[188:191], v[148:151], v[128:143]
	ds_read_b64_tr_b16 v[100:101], v209 offset:30720
	ds_read_b64_tr_b16 v[102:103], v209 offset:31232
	v_add_f32_e32 v65, v86, v65
	v_add_f32_e32 v65, v87, v65
	v_add_f32_e32 v65, v88, v65
	v_add_f32_e32 v65, v89, v65
	v_cvt_pk_bf16_f32 v166, v84, v85
	v_cvt_pk_bf16_f32 v167, v86, v87
	s_waitcnt lgkmcnt(14)
	v_mfma_f32_32x32x16_bf16 v[112:127], v[184:187], v[148:151], v[112:127]
	ds_read_b64_tr_b16 v[96:97], v209 offset:27648
	ds_read_b64_tr_b16 v[98:99], v209 offset:28160
	v_add_f32_e32 v65, v90, v65
	v_add_f32_e32 v65, v91, v65
	v_add_f32_e32 v65, v92, v65
	v_add_f32_e32 v65, v93, v65
	v_cvt_pk_bf16_f32 v160, v88, v89
	v_cvt_pk_bf16_f32 v161, v90, v91
	s_waitcnt lgkmcnt(14)
	v_mfma_f32_32x32x16_bf16 v[128:143], v[180:183], v[144:147], v[128:143]
	ds_read_b64_tr_b16 v[86:87], v209 offset:31744
	ds_read_b64_tr_b16 v[88:89], v209 offset:32256
	v_add_f32_e32 v65, v94, v65
	v_add_f32_e32 v65, v95, v65
	v_add_f32_e32 v65, 0, v65
	v_cvt_pk_bf16_f32 v162, v92, v93
	v_cvt_pk_bf16_f32 v163, v94, v95
	v_mfma_f32_32x32x16_bf16 v[112:127], v[176:179], v[144:147], v[112:127]
	v_lshl_add_u64 v[190:191], v[212:213], 0, s[48:49]
	v_lshl_add_u64 v[78:79], v[190:191], 0, s[10:11]
	s_add_i32 s5, s42, s3
	s_mov_b32 s6, m0
	s_mov_b32 m0, s5
	s_nop 0
	global_load_lds_dwordx4 v[78:79], off
	s_mov_b32 m0, s6
	v_lshl_add_u64 v[188:189], v[210:211], 0, s[48:49]
	v_lshl_add_u64 v[78:79], v[188:189], 0, s[12:13]
	s_add_i32 s5, s36, s97
	s_mov_b32 s6, m0
	s_mov_b32 m0, s5
	s_nop 0
	global_load_lds_dwordx4 v[78:79], off
	s_mov_b32 m0, s6
	v_lshl_add_u64 v[78:79], v[188:189], 0, s[14:15]
	s_add_i32 s5, s36, s96
	s_mov_b32 s6, m0
	s_mov_b32 m0, s5
	s_nop 0
	global_load_lds_dwordx4 v[78:79], off
	s_mov_b32 m0, s6
	s_waitcnt lgkmcnt(14)
	v_mfma_f32_32x32x16_bf16 v[32:47], v[172:175], v[216:219], v[32:47]
	v_exp_f32_e32 v128, v128
	v_exp_f32_e32 v129, v129
	ds_read_b64_tr_b16 v[90:91], v209 offset:49152
	ds_read_b64_tr_b16 v[92:93], v209 offset:49664
	s_waitcnt lgkmcnt(14)
	v_mfma_f32_32x32x16_bf16 v[48:63], v[172:175], v[204:207], v[48:63]
	v_exp_f32_e32 v130, v130
	v_exp_f32_e32 v131, v131
	ds_read_b64_tr_b16 v[104:105], v209 offset:53248
	ds_read_b64_tr_b16 v[106:107], v209 offset:53760
	v_add_u32_e32 v94, s37, v250
	ds_read_b128 v[82:85], v94
	ds_read_b128 v[78:81], v94 offset:512
	s_waitcnt lgkmcnt(14)
	v_mfma_f32_32x32x16_bf16 v[32:47], v[168:171], v[74:77], v[32:47]
	v_exp_f32_e32 v132, v132
	v_exp_f32_e32 v133, v133
	ds_read_b64_tr_b16 v[108:109], v209 offset:50176
	ds_read_b64_tr_b16 v[110:111], v209 offset:50688
	ds_read_b128 v[184:187], v94 offset:2048
	ds_read_b128 v[176:179], v94 offset:2560
	v_mfma_f32_32x32x16_bf16 v[48:63], v[168:171], v[70:73], v[48:63]
	v_exp_f32_e32 v134, v134
	v_exp_f32_e32 v135, v135
	ds_read_b64_tr_b16 v[192:193], v209 offset:54272
	ds_read_b64_tr_b16 v[194:195], v209 offset:54784
	ds_read_b128 v[180:183], v94 offset:4096
	ds_read_b128 v[70:73], v94 offset:4608
	s_waitcnt lgkmcnt(14)
	v_mfma_f32_32x32x16_bf16 v[32:47], v[164:167], v[66:69], v[32:47]
	v_exp_f32_e32 v136, v136
	v_exp_f32_e32 v137, v137
	ds_read_b64_tr_b16 v[196:197], v209 offset:51200
	ds_read_b64_tr_b16 v[198:199], v209 offset:51712
	ds_read_b128 v[74:77], v94 offset:6144
	ds_read_b128 v[66:69], v94 offset:6656
	v_mfma_f32_32x32x16_bf16 v[48:63], v[164:167], v[100:103], v[48:63]
	v_exp_f32_e32 v138, v138
	v_exp_f32_e32 v139, v139
	ds_read_b64_tr_b16 v[100:101], v209 offset:55296
	ds_read_b64_tr_b16 v[102:103], v209 offset:55808
	v_mfma_f32_32x32x16_bf16 v[32:47], v[160:163], v[96:99], v[32:47]
	v_exp_f32_e32 v140, v140
	v_exp_f32_e32 v141, v141
	ds_read_b64_tr_b16 v[94:95], v209 offset:52224
	ds_read_b64_tr_b16 v[96:97], v209 offset:52736
	v_mfma_f32_32x32x16_bf16 v[48:63], v[160:163], v[86:89], v[48:63]
	v_exp_f32_e32 v142, v142
	v_exp_f32_e32 v143, v143
	ds_read_b64_tr_b16 v[86:87], v209 offset:56320
	ds_read_b64_tr_b16 v[88:89], v209 offset:56832
	s_waitcnt lgkmcnt(14)
	v_mfma_f32_32x32x16_bf16 v[0:15], v[172:175], v[90:93], v[0:15]
	v_exp_f32_e32 v112, v112
	v_exp_f32_e32 v113, v113
	v_mfma_f32_32x32x16_bf16 v[16:31], v[172:175], v[104:107], v[16:31]
	v_exp_f32_e32 v114, v114
	v_exp_f32_e32 v115, v115
	v_mfma_f32_32x32x16_bf16 v[0:15], v[168:171], v[108:111], v[0:15]
	v_exp_f32_e32 v116, v116
	v_exp_f32_e32 v117, v117
	s_waitcnt lgkmcnt(12)
	v_mfma_f32_32x32x16_bf16 v[16:31], v[168:171], v[192:195], v[16:31]
	v_exp_f32_e32 v118, v118
	v_exp_f32_e32 v119, v119
	s_waitcnt lgkmcnt(8)
	v_mfma_f32_32x32x16_bf16 v[0:15], v[164:167], v[196:199], v[0:15]
	v_exp_f32_e32 v120, v120
	v_exp_f32_e32 v121, v121
	s_waitcnt lgkmcnt(4)
	v_mfma_f32_32x32x16_bf16 v[16:31], v[164:167], v[100:103], v[16:31]
	v_exp_f32_e32 v122, v122
	v_exp_f32_e32 v123, v123
	s_waitcnt lgkmcnt(2)
	v_mfma_f32_32x32x16_bf16 v[0:15], v[160:163], v[94:97], v[0:15]
	v_exp_f32_e32 v124, v124
	v_exp_f32_e32 v125, v125
	s_waitcnt lgkmcnt(0)
	v_mfma_f32_32x32x16_bf16 v[16:31], v[160:163], v[86:89], v[16:31]
	v_exp_f32_e32 v126, v126
	v_exp_f32_e32 v127, v127
	s_waitcnt vmcnt(3) lgkmcnt(0)
	s_barrier
	s_add_i32 s5, s36, 0x2000
	s_cmpk_lg_i32 s36, 0x4000
	s_cselect_b32 s42, s5, 0
	v_add_u32_e32 v209, s1, v252
	ds_read_b64_tr_b16 v[192:193], v209 offset:24576
	ds_read_b64_tr_b16 v[194:195], v209 offset:25088
	v_mfma_f32_32x32x16_bf16 v[96:111], v[82:85], v[156:159], v[230:245]
	v_add_f32_e32 v86, v128, v129
	v_add_f32_e32 v86, v130, v86
	v_add_f32_e32 v86, v131, v86
	v_add_f32_e32 v86, v132, v86
	v_add_f32_e32 v86, v133, v86
	v_cvt_pk_bf16_f32 v172, v128, v129
	v_cvt_pk_bf16_f32 v173, v130, v131
	ds_read_b64_tr_b16 v[196:197], v209 offset:28672
	ds_read_b64_tr_b16 v[198:199], v209 offset:29184
	v_add_f32_e32 v82, v134, v86
	v_add_f32_e32 v82, v135, v82
	v_add_f32_e32 v82, v136, v82
	v_add_f32_e32 v128, v137, v82
	v_mfma_f32_32x32x16_bf16 v[80:95], v[78:81], v[156:159], v[230:245]
	v_cvt_pk_bf16_f32 v174, v132, v133
	v_cvt_pk_bf16_f32 v175, v134, v135
	ds_read_b64_tr_b16 v[216:217], v209 offset:25600
	ds_read_b64_tr_b16 v[218:219], v209 offset:26112
	v_mfma_f32_32x32x16_bf16 v[96:111], v[184:187], v[152:155], v[96:111]
	v_add_f32_e32 v78, v138, v128
	v_add_f32_e32 v78, v139, v78
	v_add_f32_e32 v78, v140, v78
	v_add_f32_e32 v78, v141, v78
	v_cvt_pk_bf16_f32 v168, v136, v137
	v_cvt_pk_bf16_f32 v169, v138, v139
	ds_read_b64_tr_b16 v[136:137], v209 offset:29696
	ds_read_b64_tr_b16 v[138:139], v209 offset:30208
	v_mfma_f32_32x32x16_bf16 v[80:95], v[176:179], v[152:155], v[80:95]
	v_add_f32_e32 v78, v142, v78
	v_add_f32_e32 v78, v143, v78
	v_add_f32_e32 v78, v112, v78
	v_add_f32_e32 v78, v113, v78
	v_cvt_pk_bf16_f32 v170, v140, v141
	v_cvt_pk_bf16_f32 v171, v142, v143
	ds_read_b64_tr_b16 v[132:133], v209 offset:26624
	ds_read_b64_tr_b16 v[134:135], v209 offset:27136
	v_mfma_f32_32x32x16_bf16 v[96:111], v[180:183], v[148:151], v[96:111]
	v_add_f32_e32 v78, v114, v78
	v_add_f32_e32 v78, v115, v78
	v_add_f32_e32 v78, v116, v78
	v_add_f32_e32 v78, v117, v78
	v_cvt_pk_bf16_f32 v164, v112, v113
	v_cvt_pk_bf16_f32 v165, v114, v115
	ds_read_b64_tr_b16 v[128:129], v209 offset:30720
	ds_read_b64_tr_b16 v[130:131], v209 offset:31232
	v_mfma_f32_32x32x16_bf16 v[80:95], v[70:73], v[148:151], v[80:95]
	v_add_f32_e32 v78, v118, v78
	v_add_f32_e32 v78, v119, v78
	v_add_f32_e32 v78, v120, v78
	v_add_f32_e32 v78, v121, v78
	v_cvt_pk_bf16_f32 v166, v116, v117
	v_cvt_pk_bf16_f32 v167, v118, v119
	ds_read_b64_tr_b16 v[112:113], v209 offset:27648
	ds_read_b64_tr_b16 v[114:115], v209 offset:28160
	v_mfma_f32_32x32x16_bf16 v[96:111], v[74:77], v[144:147], v[96:111]
	v_add_f32_e32 v70, v122, v78
	v_add_f32_e32 v70, v123, v70
	v_add_f32_e32 v70, v124, v70
	v_add_f32_e32 v78, v125, v70
	v_cvt_pk_bf16_f32 v160, v120, v121
	v_cvt_pk_bf16_f32 v161, v122, v123
	ds_read_b64_tr_b16 v[70:71], v209 offset:31744
	ds_read_b64_tr_b16 v[72:73], v209 offset:32256
	v_mfma_f32_32x32x16_bf16 v[80:95], v[66:69], v[144:147], v[80:95]
	v_add_f32_e32 v74, v126, v78
	v_add_f32_e32 v74, v127, v74
	v_add_f32_e32 v74, 0, v74
	v_cvt_pk_bf16_f32 v162, v124, v125
	v_cvt_pk_bf16_f32 v163, v126, v127
	v_lshl_add_u64 v[66:67], v[190:191], 0, s[16:17]
	s_add_i32 s1, s36, s3
	s_mov_b32 s5, m0
	s_mov_b32 m0, s1
	s_nop 0
	global_load_lds_dwordx4 v[66:67], off
	s_mov_b32 m0, s5
	v_lshl_add_u64 v[66:67], v[188:189], 0, s[18:19]
	s_add_i32 s1, s42, s97
	s_mov_b32 s5, m0
	s_mov_b32 m0, s1
	s_nop 0
	global_load_lds_dwordx4 v[66:67], off
	s_mov_b32 m0, s5
	v_lshl_add_u64 v[66:67], v[188:189], 0, s[20:21]
	s_add_i32 s1, s42, s96
	s_mov_b32 s5, m0
	s_mov_b32 m0, s1
	s_nop 0
	global_load_lds_dwordx4 v[66:67], off
	s_mov_b32 m0, s5
	s_waitcnt lgkmcnt(14)
; #define WAIT_BAR(N) asm volatile("s_waitcnt vmcnt(" #N ") lgkmcnt(0)\n\ts_barrier":::"memory")
;   #define RESC() do{ if(resc){ asm volatile("s_waitcnt lgkmcnt(0)":::"memory"); \
;       _Pragma("unroll") for(int d_=0;d_<2;++d_) _Pragma("unroll") for(int r=0;r<16;++r){const float f_=wsf[crow(r,hi)];o[d_][r]*=f_;o2[d_][r]*=f_;} } }while(0)
;   #define ROT() do{sl_prev=sl_cur;sl_cur=sl_next;sl_next=(sl_next==(NSLOT-1)*SLOTB)?0:sl_next+SLOTB;}while(0)
; template<int THRL> __device__ __forceinline__ void attn_unit(int b,int h,int qb,unsigned char*wsb,char*shm,float kmax,const int CMB,float lam){
;     ...
;   int t=1;
;     ...
;   for(;t+5<NT;t+=2){
;     STEP(pB0,pB1,pA0,pA1,t,true,true,true);     WAIT_BAR(3); RESC(); ROT();
;     STEP(pA0,pA1,pB0,pB1,t+1,true,true,true);   WAIT_BAR(3); RESC(); ROT();
;   }
	v_mfma_f32_32x32x16_bf16 v[32:47], v[172:175], v[192:195], v[32:47]
	v_exp_f32_e32 v96, v96
	v_exp_f32_e32 v97, v97
	ds_read_b64_tr_b16 v[66:67], v209 offset:49152
	ds_read_b64_tr_b16 v[68:69], v209 offset:49664
	s_waitcnt lgkmcnt(14)
	v_mfma_f32_32x32x16_bf16 v[48:63], v[172:175], v[196:199], v[48:63]
	v_exp_f32_e32 v98, v98
	v_exp_f32_e32 v99, v99
	ds_read_b64_tr_b16 v[76:77], v209 offset:53248
	ds_read_b64_tr_b16 v[78:79], v209 offset:53760
	v_add_u32_e32 v75, s42, v250
	ds_read_b128 v[204:207], v75
	ds_read_b128 v[200:203], v75 offset:512
	s_waitcnt lgkmcnt(14)
	v_mfma_f32_32x32x16_bf16 v[32:47], v[168:171], v[216:219], v[32:47]
	v_exp_f32_e32 v100, v100
	v_exp_f32_e32 v101, v101
	ds_read_b64_tr_b16 v[116:117], v209 offset:50176
	ds_read_b64_tr_b16 v[118:119], v209 offset:50688
	ds_read_b128 v[196:199], v75 offset:2048
	ds_read_b128 v[192:195], v75 offset:2560
	v_mfma_f32_32x32x16_bf16 v[48:63], v[168:171], v[136:139], v[48:63]
	v_exp_f32_e32 v102, v102
	v_exp_f32_e32 v103, v103
	ds_read_b64_tr_b16 v[120:121], v209 offset:54272
	ds_read_b64_tr_b16 v[122:123], v209 offset:54784
	ds_read_b128 v[188:191], v75 offset:4096
	ds_read_b128 v[184:187], v75 offset:4608
	s_waitcnt lgkmcnt(14)
	v_mfma_f32_32x32x16_bf16 v[32:47], v[164:167], v[132:135], v[32:47]
	v_exp_f32_e32 v104, v104
	v_exp_f32_e32 v105, v105
	ds_read_b64_tr_b16 v[124:125], v209 offset:51200
	ds_read_b64_tr_b16 v[126:127], v209 offset:51712
	ds_read_b128 v[180:183], v75 offset:6144
	ds_read_b128 v[176:179], v75 offset:6656
	v_mfma_f32_32x32x16_bf16 v[48:63], v[164:167], v[128:131], v[48:63]
	v_exp_f32_e32 v106, v106
	v_exp_f32_e32 v107, v107
	ds_read_b64_tr_b16 v[128:129], v209 offset:55296
	ds_read_b64_tr_b16 v[130:131], v209 offset:55808
	v_mfma_f32_32x32x16_bf16 v[32:47], v[160:163], v[112:115], v[32:47]
	v_exp_f32_e32 v108, v108
	v_exp_f32_e32 v109, v109
	ds_read_b64_tr_b16 v[112:113], v209 offset:52224
	ds_read_b64_tr_b16 v[114:115], v209 offset:52736
	v_mfma_f32_32x32x16_bf16 v[48:63], v[160:163], v[70:73], v[48:63]
	v_exp_f32_e32 v110, v110
	v_exp_f32_e32 v111, v111
	ds_read_b64_tr_b16 v[70:71], v209 offset:56320
	ds_read_b64_tr_b16 v[72:73], v209 offset:56832
	s_waitcnt lgkmcnt(14)
	v_mfma_f32_32x32x16_bf16 v[0:15], v[172:175], v[66:69], v[0:15]
	v_exp_f32_e32 v80, v80
	v_exp_f32_e32 v81, v81
	v_mfma_f32_32x32x16_bf16 v[16:31], v[172:175], v[76:79], v[16:31]
	v_exp_f32_e32 v82, v82
	v_exp_f32_e32 v83, v83
	v_mfma_f32_32x32x16_bf16 v[0:15], v[168:171], v[116:119], v[0:15]
	v_exp_f32_e32 v84, v84
	v_exp_f32_e32 v85, v85
	s_waitcnt lgkmcnt(12)
	v_mfma_f32_32x32x16_bf16 v[16:31], v[168:171], v[120:123], v[16:31]
	v_exp_f32_e32 v86, v86
	v_exp_f32_e32 v87, v87
	s_waitcnt lgkmcnt(8)
	v_mfma_f32_32x32x16_bf16 v[0:15], v[164:167], v[124:127], v[0:15]
	v_exp_f32_e32 v88, v88
	v_exp_f32_e32 v89, v89
	s_waitcnt lgkmcnt(4)
	v_mfma_f32_32x32x16_bf16 v[16:31], v[164:167], v[128:131], v[16:31]
	v_exp_f32_e32 v90, v90
	v_exp_f32_e32 v91, v91
	s_waitcnt lgkmcnt(2)
	v_mfma_f32_32x32x16_bf16 v[0:15], v[160:163], v[112:115], v[0:15]
	v_exp_f32_e32 v92, v92
	v_exp_f32_e32 v93, v93
	s_waitcnt lgkmcnt(0)
	v_mfma_f32_32x32x16_bf16 v[16:31], v[160:163], v[70:73], v[16:31]
	v_exp_f32_e32 v94, v94
	v_exp_f32_e32 v95, v95
	s_add_i32 s1, s42, 0x2000
	s_waitcnt vmcnt(3) lgkmcnt(0)
	s_barrier
	s_cmpk_lg_i32 s42, 0x4000
	v_add_f32_e32 v64, v64, v65
	s_mov_b32 s5, s36
	s_cselect_b32 s36, s1, 0
	s_add_i32 s33, s33, 2
	v_lshl_add_u64 v[210:211], v[210:211], 0, s[22:23]
	v_lshl_add_u64 v[212:213], v[212:213], 0, s[22:23]
	s_cmp_ge_u32 s33, s89
	v_add_f32_e32 v64, v64, v74
	s_cbranch_scc0 .LBB0_311
	ds_read_b32 v230, v246
	ds_read_b32 v231, v246 offset:2048
	ds_read_b32 v232, v246 offset:4096
	ds_read_b32 v233, v246 offset:6144
	ds_read_b32 v234, v246 offset:8192
	ds_read_b32 v235, v246 offset:10240
	ds_read_b32 v236, v246 offset:12288
	ds_read_b32 v237, v246 offset:14336
	ds_read_b32 v238, v246 offset:16384
	ds_read_b32 v239, v246 offset:18432
	ds_read_b32 v240, v246 offset:20480
	ds_read_b32 v241, v246 offset:22528
	ds_read_b32 v242, v246 offset:24576
	ds_read_b32 v243, v246 offset:26624
	ds_read_b32 v244, v246 offset:28672
	ds_read_b32 v245, v246 offset:30720
	ds_read_b32 v246, v246 offset:32768
	s_waitcnt lgkmcnt(0)
	s_nop 0
	s_nop 0
	s_nop 0
	s_nop 0
	s_nop 0
	s_add_i32 s6, s4, -3
	s_branch .LBB0_314
